# attention: next unit's Q/K0/K1 loads issued before this unit's output stores (prompt-to-prompt transitions), counted waits per path; epilogue temporaries moved off the staging registers
# speedup vs baseline: 1.0087x; 1.0087x over previous
; #define LAS __attribute__((address_space(3)))
; __device__ __forceinline__ int opaque_tid() { int t = threadIdx.x; asm volatile("" : "+v"(t)); return t; }
; __device__ __forceinline__ void ph_attn(const Params& p, LAS unsigned char* lds) {
;     const int tid = opaque_tid(), lane = tid & 63, w = __builtin_amdgcn_readfirstlane(tid >> 6), fr = lane & 15, fq = lane >> 4;
;     unsigned char* ws = p.ws; const bf16_t* qb = (const bf16_t*)(ws + WS_A); const bf16_t* kb = (const bf16_t*)(ws + WS_KB); const bf16_t* vt = (const bf16_t*)(ws + WS_VT); bf16_t* ao = (bf16_t*)(ws + WS_B);
;     constexpr int PR = 36864;
;     LAS unsigned char* pw = lds + PR + w * 8448 + fr * 528 + fq * 8;
;     const unsigned koff = (unsigned)((tid >> 5) * 1024 + (tid & 31) * 8);
;     const unsigned voff = (unsigned)((tid >> 3) * 256 + (tid & 7) * 8);
;     LAS unsigned char* kst = lds + (tid >> 5) * 528 + (tid & 31) * 16;
;     LAS unsigned char* vst = lds + (tid >> 3) * 144 + (tid & 7) * 16;
;     const LAS unsigned char* krd = lds + fr * 528 + fq * 16;
;     const LAS unsigned char* vrd = lds + fr * 144 + fq * 16;
; #pragma unroll 1
;     for (int u = blockIdx.x; u < 1088; u += gridDim.x) {
.LBB0_1080:
	s_cmp_lt_i32 s94, 9
	s_cselect_b64 s[0:1], -1, 0
	s_and_b64 s[4:5], s[0:1], s[4:5]
	s_andn2_b64 vcc, exec, s[4:5]
	s_cbranch_vccnz .LBB0_1110
	v_mov_b32_e32 v0, v200
	s_cmpk_gt_i32 s2, 0x43f
	s_nop 0
	v_readfirstlane_b32 s4, v0
	s_cbranch_scc1 .LBB0_1110
	s_add_u32 s6, s92, 0x11680000
	s_addc_u32 s7, s93, 0
	s_add_u32 s3, s92, 0x19c80000
	s_addc_u32 s14, s93, 0
	s_add_u32 s15, s92, 0x1a880000
	s_addc_u32 s20, s93, 0
	s_add_u32 s8, s92, 0x15780000
	s_addc_u32 s9, s93, 0
	s_ashr_i32 s4, s4, 6
	s_waitcnt lgkmcnt(0)
	v_and_b32_e32 v1, 15, v0
	s_waitcnt vmcnt(0)
	v_bfe_u32 v3, v0, 4, 2
	s_mul_i32 s5, s4, 0x2100
	v_ashrrev_i32_e32 v4, 5, v0
	v_and_b32_e32 v6, 31, v0
	v_ashrrev_i32_e32 v7, 3, v0
	v_and_b32_e32 v0, 7, v0
	s_add_i32 s10, s5, 0
	v_lshlrev_b32_e32 v11, 4, v0
	v_lshlrev_b32_e32 v0, 3, v0
	s_movk_i32 s12, 0x210
	v_mov_b32_e32 v2, s10
	s_movk_i32 s10, 0x90
	v_lshl_or_b32 v180, v7, 8, v0
	v_lshlrev_b32_e32 v0, 3, v6
	v_mad_u32_u24 v5, v1, s12, v2
	v_lshlrev_b32_e32 v2, 3, v3
	v_mul_lo_u32 v8, v4, s12
	v_mul_lo_u32 v10, v7, s10
	v_mad_u32_u24 v12, v1, s12, 0
	v_lshlrev_b32_e32 v13, 4, v3
	s_movk_i32 s10, 0xfe80
	v_lshl_or_b32 v182, v4, 10, v0
	s_lshl_b32 s21, s4, 4
	v_lshlrev_b32_e32 v4, 2, v3
	v_mov_b32_e32 v3, s5
	v_add_u32_e32 v193, v12, v13
	v_mad_i32_i24 v12, v1, s10, v12
	v_or_b32_e32 v196, s21, v1
	v_mad_u32_u24 v1, v1, s12, v3
	v_mov_b32_e32 v0, 0
	v_add3_u32 v1, v1, v13, 0
	v_add_u32_e32 v8, 0, v8
	v_lshlrev_b32_e32 v9, 4, v6
	v_add_u32_e32 v10, 0, v10
	v_mov_b32_e32 v181, v0
	v_add_u32_e32 v197, 0x9000, v1
	v_mbcnt_lo_u32_b32 v1, -1, 0
	s_mov_b32 s11, 0
	v_mov_b32_e32 v183, v0
	v_lshl_add_u64 v[184:185], v[180:181], 1, s[92:93]
	s_mov_b32 s22, 0x8000
	v_lshlrev_b32_e32 v186, 1, v2
	s_mov_b32 s23, 0x10000
	s_mov_b32 s24, 0x18000
	s_mov_b32 s25, 0x20000
	s_mov_b32 s26, 0xff61b1e6
	v_add_u32_e32 v198, v5, v2
	v_add_u32_e32 v199, v10, v11
	v_add_u32_e32 v201, v12, v13
	v_lshlrev_b32_e32 v188, 1, v4
	v_add_u32_e32 v202, v8, v9
	v_mbcnt_hi_u32_b32 v203, -1, v1
	s_mov_b32 s27, s2
	s_mov_b32 s96, 0
	v_lshrrev_b32_e32 v237, 3, v200
	v_and_b32_e32 v238, 7, v200
	v_bfe_u32 v239, v200, 4, 3
	v_xor_b32_e32 v238, v238, v239
	v_lshlrev_b32_e32 v238, 4, v238
	v_lshl_add_u32 v199, v237, 7, v238
	v_and_b32_e32 v237, 15, v200
	v_bfe_u32 v238, v200, 4, 2
	v_bfe_u32 v239, v200, 1, 3
	v_xor_b32_e32 v238, v238, v239
	v_lshlrev_b32_e32 v238, 4, v238
	v_lshl_add_u32 v201, v237, 7, v238
	v_xor_b32_e32 v239, 64, v201
	v_lshrrev_b32_e32 v237, 5, v200
	v_and_b32_e32 v238, 31, v200
	v_xor_b32_e32 v238, v238, v237
	v_lshlrev_b32_e32 v238, 4, v238
	v_lshl_add_u32 v202, v237, 9, v238
	v_and_b32_e32 v237, 15, v200
	v_bfe_u32 v238, v200, 4, 2
	v_and_b32_e32 v193, 3, v237
	v_xor_b32_e32 v238, v238, v193
	v_lshlrev_b32_e32 v238, 4, v238
	v_lshrrev_b32_e32 v193, 2, v237
	v_lshl_add_u32 v238, v193, 6, v238
	v_lshl_add_u32 v193, v237, 9, v238
	s_branch .LBB0_1084

; #define LOADK(i) do { _Pragma("unroll") for (int j = 0; j < 4; ++j) st[j] = *(const u32x4*)(kbase + ((i) * 64 + j * 16) * 1024 + koff); } while (0)
; #define LOADV(i) do { _Pragma("unroll") for (int j = 0; j < 4; ++j) st[j] = *(const u32x4*)(vbase + (j * 64 * 256 + (i) * 64) + voff); } while (0)
; #define STOREK() do { _Pragma("unroll") for (int j = 0; j < 4; ++j) *(LAS u32x4*)(kst + j * 16 * 528) = st[j]; } while (0)
; __device__ __forceinline__ void ph_attn(const Params& p, LAS unsigned char* lds) {
;     ...
;         const bool active = (w * 16) < nrows;
;         bf16x8 qf[8];
;         if (active) {
;             const bf16_t* qp = qb + (size_t)(r0 + w * 16 + fr) * D + h * 256 + fq * 8;
; #pragma unroll
;             for (int ks = 0; ks < 8; ++ks) qf[ks] = *(const bf16x8*)(qp + ks * 32);
;         }
;         u32x4 st[4];
;         const bf16_t* kbase = kb + (size_t)kvb * 256 * 1024 + h * 256; const bf16_t* vbase = vt + ((size_t)kvb * 1024 + h * 256) * 256;
;     ...
;         f32x4 sc[16];
;         LOADK(0);
; #pragma unroll
;         for (int i = 0; i < 4; ++i) {
;             __syncthreads(); STOREK(); __syncthreads();
;             if (i < 3) LOADK(i + 1); else LOADV(0);
.LBB0_1090:
	v_add_u32_e32 v190, s18, v196
	s_andn2_b64 vcc, exec, s[16:17]
	v_ashrrev_i32_e32 v191, 31, v190
	s_cbranch_vccnz .LBB0_1092
	v_lshlrev_b64 v[2:3], 11, v[190:191]
	v_lshl_add_u64 v[2:3], s[6:7], 0, v[2:3]
	s_lshl_b32 s16, s5, 9
	s_mov_b32 s17, s11
	v_lshl_add_u64 v[2:3], v[2:3], 0, s[16:17]
	v_mov_b32_e32 v187, v0
	v_lshl_add_u64 v[2:3], v[2:3], 0, v[186:187]
	s_cmp_eq_u32 s96, 1
	s_cbranch_scc1 .Lpf_skipq
	global_load_dwordx4 v[32:35], v[2:3], off
	global_load_dwordx4 v[28:31], v[2:3], off offset:64
	global_load_dwordx4 v[24:27], v[2:3], off offset:128
	global_load_dwordx4 v[20:23], v[2:3], off offset:192
	global_load_dwordx4 v[16:19], v[2:3], off offset:256
	global_load_dwordx4 v[12:15], v[2:3], off offset:320
	global_load_dwordx4 v[8:11], v[2:3], off offset:384
	global_load_dwordx4 v[4:7], v[2:3], off offset:448
.Lpf_skipq:
	s_lshl_b32 s10, s5, 8
.LBB0_1092:
	s_ashr_i32 s5, s4, 31
	s_lshl_b64 s[16:17], s[4:5], 19
	s_add_u32 s18, s3, s16
	s_addc_u32 s19, s14, s17
	s_lshl_b64 s[4:5], s[10:11], 1
	s_add_u32 s98, s18, s4
	s_addc_u32 s99, s19, s5
	s_lshl_b64 s[18:19], s[10:11], 9
	s_add_u32 s100, s15, s16
	s_addc_u32 s101, s20, s17
	s_add_u32 s100, s100, s18
	s_addc_u32 s101, s101, s19
	v_lshlrev_b32_e32 v237, 1, v182
	v_lshlrev_b32_e32 v238, 1, v180
	v_xor_b32_e32 v124, 64, v193
	v_xor_b32_e32 v125, 0x80, v193
	v_xor_b32_e32 v126, 0xc0, v193
	s_cmp_eq_u32 s96, 1
	s_cbranch_scc1 .Lpf_start
	v_mov_b32_e32 v100, v237
	v_add_u32_e32 v104, 0x8000, v237
	v_add_u32_e32 v108, 0x10000, v237
	v_add_u32_e32 v112, 0x18000, v237
	global_load_dwordx4 v[100:103], v100, s[98:99]
	global_load_dwordx4 v[104:107], v104, s[98:99]
	global_load_dwordx4 v[108:111], v108, s[98:99]
	global_load_dwordx4 v[112:115], v112, s[98:99]
	v_add_u32_e32 v240, 0x20000, v237
	v_add_u32_e32 v244, 0x28000, v237
	v_add_u32_e32 v248, 0x30000, v237
	v_add_u32_e32 v252, 0x38000, v237
	global_load_dwordx4 v[240:243], v240, s[98:99]
	global_load_dwordx4 v[244:247], v244, s[98:99]
	global_load_dwordx4 v[248:251], v248, s[98:99]
	global_load_dwordx4 v[252:255], v252, s[98:99]
	s_barrier
	s_waitcnt vmcnt(7)
	ds_write_b128 v202, v[100:103]
	s_waitcnt vmcnt(6)
	ds_write_b128 v202, v[104:107] offset:8192
	s_waitcnt vmcnt(5)
	ds_write_b128 v202, v[108:111] offset:16384
	s_waitcnt vmcnt(4)
	ds_write_b128 v202, v[112:115] offset:24576
	s_branch .Lpf_join0
	.Lpf_start:
	s_barrier
	s_waitcnt vmcnt(23)
	ds_write_b128 v202, v[100:103]
	s_waitcnt vmcnt(22)
	ds_write_b128 v202, v[104:107] offset:8192
	s_waitcnt vmcnt(21)
	ds_write_b128 v202, v[108:111] offset:16384
	s_waitcnt vmcnt(20)
	ds_write_b128 v202, v[112:115] offset:24576
	.Lpf_join0:
	v_add_u32_e32 v100, 0x40000, v237
	v_add_u32_e32 v104, 0x48000, v237
	v_add_u32_e32 v108, 0x50000, v237
	v_add_u32_e32 v112, 0x58000, v237
	s_waitcnt lgkmcnt(0)
	s_barrier
	global_load_dwordx4 v[100:103], v100, s[98:99]
	global_load_dwordx4 v[104:107], v104, s[98:99]
	global_load_dwordx4 v[108:111], v108, s[98:99]
	global_load_dwordx4 v[112:115], v112, s[98:99]
	s_and_b64 vcc, exec, s[12:13]
	s_cbranch_vccz .LBB0_1094
	ds_read_b128 v[128:131], v193
	ds_read_b128 v[132:135], v193 offset:8192
	ds_read_b128 v[136:139], v193 offset:16384
	ds_read_b128 v[140:143], v193 offset:24576
	ds_read_b128 v[144:147], v124
	ds_read_b128 v[148:151], v124 offset:8192
	ds_read_b128 v[152:155], v124 offset:16384
	ds_read_b128 v[156:159], v124 offset:24576
	s_waitcnt lgkmcnt(7)
	v_mfma_f32_16x16x32_bf16 v[48:51], v[128:131], v[32:35], 0
	ds_read_b128 v[160:163], v125
	s_waitcnt lgkmcnt(7)
	v_mfma_f32_16x16x32_bf16 v[64:67], v[132:135], v[32:35], 0
	ds_read_b128 v[164:167], v125 offset:8192
	s_waitcnt lgkmcnt(7)
	v_mfma_f32_16x16x32_bf16 v[80:83], v[136:139], v[32:35], 0
	ds_read_b128 v[168:171], v125 offset:16384
	s_waitcnt lgkmcnt(7)
	v_mfma_f32_16x16x32_bf16 v[96:99], v[140:143], v[32:35], 0
	ds_read_b128 v[172:175], v125 offset:24576
	s_waitcnt lgkmcnt(7)
	v_mfma_f32_16x16x32_bf16 v[48:51], v[144:147], v[28:31], v[48:51]
	ds_read_b128 v[176:179], v126
	s_waitcnt lgkmcnt(7)
	v_mfma_f32_16x16x32_bf16 v[64:67], v[148:151], v[28:31], v[64:67]
	ds_read_b128 v[128:131], v126 offset:8192
	s_waitcnt lgkmcnt(7)
	v_mfma_f32_16x16x32_bf16 v[80:83], v[152:155], v[28:31], v[80:83]
	ds_read_b128 v[132:135], v126 offset:16384
	s_waitcnt lgkmcnt(7)
	v_mfma_f32_16x16x32_bf16 v[96:99], v[156:159], v[28:31], v[96:99]
	ds_read_b128 v[136:139], v126 offset:24576
	s_waitcnt lgkmcnt(7)
	v_mfma_f32_16x16x32_bf16 v[48:51], v[160:163], v[24:27], v[48:51]
	ds_read_b128 v[140:143], v193 offset:256
	s_waitcnt lgkmcnt(7)
	v_mfma_f32_16x16x32_bf16 v[64:67], v[164:167], v[24:27], v[64:67]
	ds_read_b128 v[144:147], v193 offset:8448
	s_waitcnt lgkmcnt(7)
	v_mfma_f32_16x16x32_bf16 v[80:83], v[168:171], v[24:27], v[80:83]
	ds_read_b128 v[148:151], v193 offset:16640
	s_waitcnt lgkmcnt(7)
	v_mfma_f32_16x16x32_bf16 v[96:99], v[172:175], v[24:27], v[96:99]
	ds_read_b128 v[152:155], v193 offset:24832
	s_waitcnt lgkmcnt(7)
	v_mfma_f32_16x16x32_bf16 v[48:51], v[176:179], v[20:23], v[48:51]
	ds_read_b128 v[156:159], v124 offset:256
	s_waitcnt lgkmcnt(7)
	v_mfma_f32_16x16x32_bf16 v[64:67], v[128:131], v[20:23], v[64:67]
	ds_read_b128 v[160:163], v124 offset:8448
	s_waitcnt lgkmcnt(7)
	v_mfma_f32_16x16x32_bf16 v[80:83], v[132:135], v[20:23], v[80:83]
	ds_read_b128 v[164:167], v124 offset:16640
	s_waitcnt lgkmcnt(7)
	v_mfma_f32_16x16x32_bf16 v[96:99], v[136:139], v[20:23], v[96:99]
	ds_read_b128 v[168:171], v124 offset:24832
	s_waitcnt lgkmcnt(7)
	v_mfma_f32_16x16x32_bf16 v[48:51], v[140:143], v[16:19], v[48:51]
	ds_read_b128 v[172:175], v125 offset:256
	s_waitcnt lgkmcnt(7)
; #define LAS __attribute__((address_space(3)))
; #define LOADK(i) do { _Pragma("unroll") for (int j = 0; j < 4; ++j) st[j] = *(const u32x4*)(kbase + ((i) * 64 + j * 16) * 1024 + koff); } while (0)
; #define LOADV(i) do { _Pragma("unroll") for (int j = 0; j < 4; ++j) st[j] = *(const u32x4*)(vbase + (j * 64 * 256 + (i) * 64) + voff); } while (0)
; #define STOREK() do { _Pragma("unroll") for (int j = 0; j < 4; ++j) *(LAS u32x4*)(kst + j * 16 * 528) = st[j]; } while (0)
; __device__ __forceinline__ void ph_attn(const Params& p, LAS unsigned char* lds) {
;     ...
;         for (int i = 0; i < 4; ++i) {
;             __syncthreads(); STOREK(); __syncthreads();
;             if (i < 3) LOADK(i + 1); else LOADV(0);
;             if (active) {
; #pragma unroll
;                 for (int sub = 0; sub < 4; ++sub) {
;                     f32x4 a = {0.f, 0.f, 0.f, 0.f};
; #pragma unroll
;                     for (int ks = 0; ks < 8; ++ks) {
;                         const bf16x8 kf = *(const LAS bf16x8*)(krd + sub * 16 * 528 + ks * 64);
;                         a = __builtin_amdgcn_mfma_f32_16x16x32_bf16(kf, qf[ks], a, 0, 0, 0);
;                     }
;                     sc[i * 4 + sub] = a;
;                 }
	v_mfma_f32_16x16x32_bf16 v[64:67], v[144:147], v[16:19], v[64:67]
	ds_read_b128 v[176:179], v125 offset:8448
	s_waitcnt lgkmcnt(7)
	v_mfma_f32_16x16x32_bf16 v[80:83], v[148:151], v[16:19], v[80:83]
	ds_read_b128 v[128:131], v125 offset:16640
	s_waitcnt lgkmcnt(7)
	v_mfma_f32_16x16x32_bf16 v[96:99], v[152:155], v[16:19], v[96:99]
	ds_read_b128 v[132:135], v125 offset:24832
	s_waitcnt lgkmcnt(7)
	v_mfma_f32_16x16x32_bf16 v[48:51], v[156:159], v[12:15], v[48:51]
	ds_read_b128 v[136:139], v126 offset:256
	s_waitcnt lgkmcnt(7)
	v_mfma_f32_16x16x32_bf16 v[64:67], v[160:163], v[12:15], v[64:67]
	ds_read_b128 v[140:143], v126 offset:8448
	s_waitcnt lgkmcnt(7)
	v_mfma_f32_16x16x32_bf16 v[80:83], v[164:167], v[12:15], v[80:83]
	ds_read_b128 v[144:147], v126 offset:16640
	s_waitcnt lgkmcnt(7)
	v_mfma_f32_16x16x32_bf16 v[96:99], v[168:171], v[12:15], v[96:99]
	ds_read_b128 v[148:151], v126 offset:24832
	s_waitcnt lgkmcnt(7)
	v_mfma_f32_16x16x32_bf16 v[48:51], v[172:175], v[8:11], v[48:51]
	s_waitcnt lgkmcnt(6)
	v_mfma_f32_16x16x32_bf16 v[64:67], v[176:179], v[8:11], v[64:67]
	s_waitcnt lgkmcnt(5)
	v_mfma_f32_16x16x32_bf16 v[80:83], v[128:131], v[8:11], v[80:83]
	s_waitcnt lgkmcnt(4)
	v_mfma_f32_16x16x32_bf16 v[96:99], v[132:135], v[8:11], v[96:99]
	s_waitcnt lgkmcnt(3)
	v_mfma_f32_16x16x32_bf16 v[48:51], v[136:139], v[4:7], v[48:51]
	s_waitcnt lgkmcnt(2)
	v_mfma_f32_16x16x32_bf16 v[64:67], v[140:143], v[4:7], v[64:67]
	s_waitcnt lgkmcnt(1)
	v_mfma_f32_16x16x32_bf16 v[80:83], v[144:147], v[4:7], v[80:83]
	s_waitcnt lgkmcnt(0)
	v_mfma_f32_16x16x32_bf16 v[96:99], v[148:151], v[4:7], v[96:99]
.LBB0_1094:
	s_barrier
	s_cmp_eq_u32 s96, 1
	s_cbranch_scc1 .Lpf_v0
	s_waitcnt vmcnt(7)
	ds_write_b128 v202, v[240:243]
	s_waitcnt vmcnt(6)
	ds_write_b128 v202, v[244:247] offset:8192
	s_waitcnt vmcnt(5)
	ds_write_b128 v202, v[248:251] offset:16384
	s_waitcnt vmcnt(4)
	ds_write_b128 v202, v[252:255] offset:24576
	s_branch .Lpf_j0
	.Lpf_v0:
	s_waitcnt vmcnt(23)
	ds_write_b128 v202, v[240:243]
	s_waitcnt vmcnt(22)
	ds_write_b128 v202, v[244:247] offset:8192
	s_waitcnt vmcnt(21)
	ds_write_b128 v202, v[248:251] offset:16384
	s_waitcnt vmcnt(20)
	ds_write_b128 v202, v[252:255] offset:24576
	.Lpf_j0:
	v_add_u32_e32 v240, 0x60000, v237
	v_add_u32_e32 v244, 0x68000, v237
	v_add_u32_e32 v248, 0x70000, v237
	v_add_u32_e32 v252, 0x78000, v237
	s_waitcnt lgkmcnt(0)
	s_barrier
	global_load_dwordx4 v[240:243], v240, s[98:99]
	global_load_dwordx4 v[244:247], v244, s[98:99]
	global_load_dwordx4 v[248:251], v248, s[98:99]
	global_load_dwordx4 v[252:255], v252, s[98:99]
	v_cndmask_b32_e64 v1, 0, 1, s[12:13]
	v_cmp_ne_u32_e64 s[4:5], 1, v1
	s_andn2_b64 vcc, exec, s[12:13]
	s_cbranch_vccnz .LBB0_1096
	ds_read_b128 v[128:131], v193
	ds_read_b128 v[132:135], v193 offset:8192
	ds_read_b128 v[136:139], v193 offset:16384
	ds_read_b128 v[140:143], v193 offset:24576
	ds_read_b128 v[144:147], v124
	ds_read_b128 v[148:151], v124 offset:8192
	ds_read_b128 v[152:155], v124 offset:16384
	ds_read_b128 v[156:159], v124 offset:24576
	s_waitcnt lgkmcnt(7)
	v_mfma_f32_16x16x32_bf16 v[44:47], v[128:131], v[32:35], 0
	ds_read_b128 v[160:163], v125
	s_waitcnt lgkmcnt(7)
	v_mfma_f32_16x16x32_bf16 v[60:63], v[132:135], v[32:35], 0
	ds_read_b128 v[164:167], v125 offset:8192
	s_waitcnt lgkmcnt(7)
	v_mfma_f32_16x16x32_bf16 v[76:79], v[136:139], v[32:35], 0
	ds_read_b128 v[168:171], v125 offset:16384
	s_waitcnt lgkmcnt(7)
	v_mfma_f32_16x16x32_bf16 v[92:95], v[140:143], v[32:35], 0
	ds_read_b128 v[172:175], v125 offset:24576
	s_waitcnt lgkmcnt(7)
	v_mfma_f32_16x16x32_bf16 v[44:47], v[144:147], v[28:31], v[44:47]
	ds_read_b128 v[176:179], v126
	s_waitcnt lgkmcnt(7)
	v_mfma_f32_16x16x32_bf16 v[60:63], v[148:151], v[28:31], v[60:63]
	ds_read_b128 v[128:131], v126 offset:8192
	s_waitcnt lgkmcnt(7)
	v_mfma_f32_16x16x32_bf16 v[76:79], v[152:155], v[28:31], v[76:79]
	ds_read_b128 v[132:135], v126 offset:16384
	s_waitcnt lgkmcnt(7)
	v_mfma_f32_16x16x32_bf16 v[92:95], v[156:159], v[28:31], v[92:95]
	ds_read_b128 v[136:139], v126 offset:24576
	s_waitcnt lgkmcnt(7)
	v_mfma_f32_16x16x32_bf16 v[44:47], v[160:163], v[24:27], v[44:47]
	ds_read_b128 v[140:143], v193 offset:256
	s_waitcnt lgkmcnt(7)
	v_mfma_f32_16x16x32_bf16 v[60:63], v[164:167], v[24:27], v[60:63]
	ds_read_b128 v[144:147], v193 offset:8448
	s_waitcnt lgkmcnt(7)
	v_mfma_f32_16x16x32_bf16 v[76:79], v[168:171], v[24:27], v[76:79]
	ds_read_b128 v[148:151], v193 offset:16640
	s_waitcnt lgkmcnt(7)
	v_mfma_f32_16x16x32_bf16 v[92:95], v[172:175], v[24:27], v[92:95]
	ds_read_b128 v[152:155], v193 offset:24832
	s_waitcnt lgkmcnt(7)
	v_mfma_f32_16x16x32_bf16 v[44:47], v[176:179], v[20:23], v[44:47]
	ds_read_b128 v[156:159], v124 offset:256
	s_waitcnt lgkmcnt(7)
	v_mfma_f32_16x16x32_bf16 v[60:63], v[128:131], v[20:23], v[60:63]
	ds_read_b128 v[160:163], v124 offset:8448
	s_waitcnt lgkmcnt(7)
	v_mfma_f32_16x16x32_bf16 v[76:79], v[132:135], v[20:23], v[76:79]
	ds_read_b128 v[164:167], v124 offset:16640
	s_waitcnt lgkmcnt(7)
	v_mfma_f32_16x16x32_bf16 v[92:95], v[136:139], v[20:23], v[92:95]
	ds_read_b128 v[168:171], v124 offset:24832
	s_waitcnt lgkmcnt(7)
	v_mfma_f32_16x16x32_bf16 v[44:47], v[140:143], v[16:19], v[44:47]
	ds_read_b128 v[172:175], v125 offset:256
	s_waitcnt lgkmcnt(7)
	v_mfma_f32_16x16x32_bf16 v[60:63], v[144:147], v[16:19], v[60:63]
	ds_read_b128 v[176:179], v125 offset:8448
	s_waitcnt lgkmcnt(7)
	v_mfma_f32_16x16x32_bf16 v[76:79], v[148:151], v[16:19], v[76:79]
	ds_read_b128 v[128:131], v125 offset:16640
	s_waitcnt lgkmcnt(7)
	v_mfma_f32_16x16x32_bf16 v[92:95], v[152:155], v[16:19], v[92:95]
	ds_read_b128 v[132:135], v125 offset:24832
	s_waitcnt lgkmcnt(7)
	v_mfma_f32_16x16x32_bf16 v[44:47], v[156:159], v[12:15], v[44:47]
	ds_read_b128 v[136:139], v126 offset:256
	s_waitcnt lgkmcnt(7)
	v_mfma_f32_16x16x32_bf16 v[60:63], v[160:163], v[12:15], v[60:63]
	ds_read_b128 v[140:143], v126 offset:8448
	s_waitcnt lgkmcnt(7)
	v_mfma_f32_16x16x32_bf16 v[76:79], v[164:167], v[12:15], v[76:79]
	ds_read_b128 v[144:147], v126 offset:16640
	s_waitcnt lgkmcnt(7)
	v_mfma_f32_16x16x32_bf16 v[92:95], v[168:171], v[12:15], v[92:95]
	ds_read_b128 v[148:151], v126 offset:24832
	s_waitcnt lgkmcnt(7)
	v_mfma_f32_16x16x32_bf16 v[44:47], v[172:175], v[8:11], v[44:47]
	s_waitcnt lgkmcnt(6)
	v_mfma_f32_16x16x32_bf16 v[60:63], v[176:179], v[8:11], v[60:63]
	s_waitcnt lgkmcnt(5)
	v_mfma_f32_16x16x32_bf16 v[76:79], v[128:131], v[8:11], v[76:79]
	s_waitcnt lgkmcnt(4)
	v_mfma_f32_16x16x32_bf16 v[92:95], v[132:135], v[8:11], v[92:95]
	s_waitcnt lgkmcnt(3)
	v_mfma_f32_16x16x32_bf16 v[44:47], v[136:139], v[4:7], v[44:47]
	s_waitcnt lgkmcnt(2)
	v_mfma_f32_16x16x32_bf16 v[60:63], v[140:143], v[4:7], v[60:63]
	s_waitcnt lgkmcnt(1)
	v_mfma_f32_16x16x32_bf16 v[76:79], v[144:147], v[4:7], v[76:79]
	s_waitcnt lgkmcnt(0)
	v_mfma_f32_16x16x32_bf16 v[92:95], v[148:151], v[4:7], v[92:95]

; #define LAS __attribute__((address_space(3)))
; #define LOADV(i) do { _Pragma("unroll") for (int j = 0; j < 4; ++j) st[j] = *(const u32x4*)(vbase + (j * 64 * 256 + (i) * 64) + voff); } while (0)
; #define STOREV() do { _Pragma("unroll") for (int j = 0; j < 4; ++j) *(LAS u32x4*)(vst + j * 64 * 144) = st[j]; } while (0)
; __device__ __forceinline__ void ph_attn(const Params& p, LAS unsigned char* lds) {
;     ...
;         if (active) {
;             const bf16_t* qp = qb + (size_t)(r0 + w * 16 + fr) * D + h * 256 + fq * 8;
; #pragma unroll
;             for (int ks = 0; ks < 8; ++ks) qf[ks] = *(const bf16x8*)(qp + ks * 32);
;     ...
; #pragma unroll 1
;         for (int i = 0; i < 4; ++i) {
;             __syncthreads(); STOREV(); __syncthreads();
;             if (i < 3) LOADV(i + 1);
;             if (active) {
; #pragma unroll
;                 for (int ks = 0; ks < 2; ++ks) {
;                     const bf16x8 pf = *(const LAS bf16x8*)(pw + fq * 8 + i * 128 + ks * 64);
; #pragma unroll
;                     for (int dt = 0; dt < 16; ++dt) {
;                         const bf16x8 vf = *(const LAS bf16x8*)(vrd + dt * 16 * 144 + ks * 64);
;                         oa[dt] = __builtin_amdgcn_mfma_f32_16x16x32_bf16(vf, pf, oa[dt], 0, 0, 0);
;                     }
;                 }
.Lat_pv1:
	s_waitcnt lgkmcnt(0)
	s_barrier
	s_waitcnt vmcnt(7)
	ds_write_b128 v199, v[240:243]
	s_waitcnt vmcnt(6)
	ds_write_b128 v199, v[244:247] offset:8192
	s_waitcnt vmcnt(5)
	ds_write_b128 v199, v[248:251] offset:16384
	s_waitcnt vmcnt(4)
	ds_write_b128 v199, v[252:255] offset:24576
	v_mov_b32_e32 v240, v238
	v_add_u32_e32 v244, 0x8000, v238
	v_add_u32_e32 v248, 0x10000, v238
	v_add_u32_e32 v252, 0x18000, v238
	s_waitcnt lgkmcnt(0)
	s_barrier
	global_load_dwordx4 v[240:243], v240, s[100:101] offset:384
	global_load_dwordx4 v[244:247], v244, s[100:101] offset:384
	global_load_dwordx4 v[248:251], v248, s[100:101] offset:384
	global_load_dwordx4 v[252:255], v252, s[100:101] offset:384
	s_add_i32 s97, s27, s34
	s_cmpk_lt_i32 s97, 0x400
	s_cselect_b32 s96, 1, 0
	s_cmpk_lg_i32 s34, 0x100
	s_cselect_b32 s96, 0, s96
	s_cmp_eq_u32 s96, 0
	s_cbranch_scc1 .Lpf_noq
	v_lshlrev_b64 v[2:3], 11, v[190:191]
	v_lshl_add_u64 v[2:3], s[6:7], 0, v[2:3]
	v_lshl_add_u64 v[2:3], s[10:11], 1, v[2:3]
	v_add_co_u32_e32 v2, vcc, v186, v2
	s_nop 1
	v_addc_co_u32_e32 v3, vcc, 0, v3, vcc
	v_add_co_u32_e32 v2, vcc, 0x1000000, v2
	s_nop 1
	v_addc_co_u32_e32 v3, vcc, 0, v3, vcc
	global_load_dwordx4 v[32:35], v[2:3], off
	global_load_dwordx4 v[28:31], v[2:3], off offset:64
	global_load_dwordx4 v[24:27], v[2:3], off offset:128
	global_load_dwordx4 v[20:23], v[2:3], off offset:192
	global_load_dwordx4 v[16:19], v[2:3], off offset:256
	global_load_dwordx4 v[12:15], v[2:3], off offset:320
	global_load_dwordx4 v[8:11], v[2:3], off offset:384
	global_load_dwordx4 v[4:7], v[2:3], off offset:448
	.Lpf_noq:
	s_and_b64 vcc, exec, s[4:5]
	s_cbranch_vccnz .Lat_pv2
	ds_read_b128 v[208:211], v187 offset:128
	ds_read_b128 v[212:215], v187 offset:192
	ds_read_b128 v[36:39], v201
	ds_read_b128 v[40:43], v201 offset:2048
	ds_read_b128 v[44:47], v201 offset:4096
	ds_read_b128 v[48:51], v201 offset:6144
	ds_read_b128 v[52:55], v201 offset:8192
	ds_read_b128 v[56:59], v201 offset:10240
	ds_read_b128 v[60:63], v201 offset:12288
	ds_read_b128 v[64:67], v201 offset:14336
	s_waitcnt lgkmcnt(7)
	v_mfma_f32_16x16x32_bf16 v[176:179], v[36:39], v[208:211], v[176:179]
	ds_read_b128 v[68:71], v201 offset:16384
	s_waitcnt lgkmcnt(7)
	v_mfma_f32_16x16x32_bf16 v[172:175], v[40:43], v[208:211], v[172:175]
	ds_read_b128 v[72:75], v201 offset:18432
	s_waitcnt lgkmcnt(7)
	v_mfma_f32_16x16x32_bf16 v[168:171], v[44:47], v[208:211], v[168:171]
	ds_read_b128 v[76:79], v201 offset:20480
	s_waitcnt lgkmcnt(7)
	v_mfma_f32_16x16x32_bf16 v[164:167], v[48:51], v[208:211], v[164:167]
	ds_read_b128 v[80:83], v201 offset:22528
	s_waitcnt lgkmcnt(7)
	v_mfma_f32_16x16x32_bf16 v[160:163], v[52:55], v[208:211], v[160:163]
	ds_read_b128 v[84:87], v201 offset:24576
	s_waitcnt lgkmcnt(7)
	v_mfma_f32_16x16x32_bf16 v[156:159], v[56:59], v[208:211], v[156:159]
	ds_read_b128 v[88:91], v201 offset:26624
	s_waitcnt lgkmcnt(7)
	v_mfma_f32_16x16x32_bf16 v[152:155], v[60:63], v[208:211], v[152:155]
	ds_read_b128 v[92:95], v201 offset:28672
	s_waitcnt lgkmcnt(7)
	v_mfma_f32_16x16x32_bf16 v[148:151], v[64:67], v[208:211], v[148:151]
	ds_read_b128 v[96:99], v201 offset:30720
	s_waitcnt lgkmcnt(7)
	v_mfma_f32_16x16x32_bf16 v[144:147], v[68:71], v[208:211], v[144:147]
	ds_read_b128 v[36:39], v239
	s_waitcnt lgkmcnt(7)
	v_mfma_f32_16x16x32_bf16 v[140:143], v[72:75], v[208:211], v[140:143]
	ds_read_b128 v[40:43], v239 offset:2048
	s_waitcnt lgkmcnt(7)
	v_mfma_f32_16x16x32_bf16 v[136:139], v[76:79], v[208:211], v[136:139]
	ds_read_b128 v[44:47], v239 offset:4096
	s_waitcnt lgkmcnt(7)
	v_mfma_f32_16x16x32_bf16 v[132:135], v[80:83], v[208:211], v[132:135]
	ds_read_b128 v[48:51], v239 offset:6144
	s_waitcnt lgkmcnt(7)
	v_mfma_f32_16x16x32_bf16 v[128:131], v[84:87], v[208:211], v[128:131]
	ds_read_b128 v[52:55], v239 offset:8192
	s_waitcnt lgkmcnt(7)
	v_mfma_f32_16x16x32_bf16 v[124:127], v[88:91], v[208:211], v[124:127]
	ds_read_b128 v[56:59], v239 offset:10240
	s_waitcnt lgkmcnt(7)
	v_mfma_f32_16x16x32_bf16 v[120:123], v[92:95], v[208:211], v[120:123]
	ds_read_b128 v[60:63], v239 offset:12288
	s_waitcnt lgkmcnt(7)
	v_mfma_f32_16x16x32_bf16 v[116:119], v[96:99], v[208:211], v[116:119]
	ds_read_b128 v[64:67], v239 offset:14336
	s_waitcnt lgkmcnt(7)
	v_mfma_f32_16x16x32_bf16 v[176:179], v[36:39], v[212:215], v[176:179]
	ds_read_b128 v[68:71], v239 offset:16384
	s_waitcnt lgkmcnt(7)
	v_mfma_f32_16x16x32_bf16 v[172:175], v[40:43], v[212:215], v[172:175]
	ds_read_b128 v[72:75], v239 offset:18432
	s_waitcnt lgkmcnt(7)
	v_mfma_f32_16x16x32_bf16 v[168:171], v[44:47], v[212:215], v[168:171]
	ds_read_b128 v[76:79], v239 offset:20480
	s_waitcnt lgkmcnt(7)
	v_mfma_f32_16x16x32_bf16 v[164:167], v[48:51], v[212:215], v[164:167]
	ds_read_b128 v[80:83], v239 offset:22528
	s_waitcnt lgkmcnt(7)
	v_mfma_f32_16x16x32_bf16 v[160:163], v[52:55], v[212:215], v[160:163]
	ds_read_b128 v[84:87], v239 offset:24576
	s_waitcnt lgkmcnt(7)
	v_mfma_f32_16x16x32_bf16 v[156:159], v[56:59], v[212:215], v[156:159]
	ds_read_b128 v[88:91], v239 offset:26624
	s_waitcnt lgkmcnt(7)
	v_mfma_f32_16x16x32_bf16 v[152:155], v[60:63], v[212:215], v[152:155]
	ds_read_b128 v[92:95], v239 offset:28672
	s_waitcnt lgkmcnt(7)
	v_mfma_f32_16x16x32_bf16 v[148:151], v[64:67], v[212:215], v[148:151]
	ds_read_b128 v[96:99], v239 offset:30720
	s_waitcnt lgkmcnt(7)
	v_mfma_f32_16x16x32_bf16 v[144:147], v[68:71], v[212:215], v[144:147]
	s_waitcnt lgkmcnt(6)
	v_mfma_f32_16x16x32_bf16 v[140:143], v[72:75], v[212:215], v[140:143]
	s_waitcnt lgkmcnt(5)
	v_mfma_f32_16x16x32_bf16 v[136:139], v[76:79], v[212:215], v[136:139]
	s_waitcnt lgkmcnt(4)
	v_mfma_f32_16x16x32_bf16 v[132:135], v[80:83], v[212:215], v[132:135]
	s_waitcnt lgkmcnt(3)
	v_mfma_f32_16x16x32_bf16 v[128:131], v[84:87], v[212:215], v[128:131]
	s_waitcnt lgkmcnt(2)
	v_mfma_f32_16x16x32_bf16 v[124:127], v[88:91], v[212:215], v[124:127]
	s_waitcnt lgkmcnt(1)
	v_mfma_f32_16x16x32_bf16 v[120:123], v[92:95], v[212:215], v[120:123]
	s_waitcnt lgkmcnt(0)
	v_mfma_f32_16x16x32_bf16 v[116:119], v[96:99], v[212:215], v[116:119]
; #define LAS __attribute__((address_space(3)))
; #define LOADV(i) do { _Pragma("unroll") for (int j = 0; j < 4; ++j) st[j] = *(const u32x4*)(vbase + (j * 64 * 256 + (i) * 64) + voff); } while (0)
; #define STOREV() do { _Pragma("unroll") for (int j = 0; j < 4; ++j) *(LAS u32x4*)(vst + j * 64 * 144) = st[j]; } while (0)
; __device__ __forceinline__ void ph_attn(const Params& p, LAS unsigned char* lds) {
;     ...
; #pragma unroll 1
;         for (int i = 0; i < 4; ++i) {
;             __syncthreads(); STOREV(); __syncthreads();
;             if (i < 3) LOADV(i + 1);
;             if (active) {
; #pragma unroll
;                 for (int ks = 0; ks < 2; ++ks) {
;                     const bf16x8 pf = *(const LAS bf16x8*)(pw + fq * 8 + i * 128 + ks * 64);
; #pragma unroll
;                     for (int dt = 0; dt < 16; ++dt) {
;                         const bf16x8 vf = *(const LAS bf16x8*)(vrd + dt * 16 * 144 + ks * 64);
;                         oa[dt] = __builtin_amdgcn_mfma_f32_16x16x32_bf16(vf, pf, oa[dt], 0, 0, 0);
;                     }
;                 }
.Lat_pv2:
	s_waitcnt lgkmcnt(0)
	s_barrier
	s_cmp_eq_u32 s96, 1
	s_cbranch_scc1 .Lpf_v1
	s_waitcnt vmcnt(7)
	ds_write_b128 v199, v[100:103]
	s_waitcnt vmcnt(6)
	ds_write_b128 v199, v[104:107] offset:8192
	s_waitcnt vmcnt(5)
	ds_write_b128 v199, v[108:111] offset:16384
	s_waitcnt vmcnt(4)
	ds_write_b128 v199, v[112:115] offset:24576
	s_branch .Lpf_j1
	.Lpf_v1:
	s_waitcnt vmcnt(15)
	ds_write_b128 v199, v[100:103]
	s_waitcnt vmcnt(14)
	ds_write_b128 v199, v[104:107] offset:8192
	s_waitcnt vmcnt(13)
	ds_write_b128 v199, v[108:111] offset:16384
	s_waitcnt vmcnt(12)
	ds_write_b128 v199, v[112:115] offset:24576
	.Lpf_j1:
	s_waitcnt lgkmcnt(0)
	s_barrier
	s_cmp_eq_u32 s96, 0
	s_cbranch_scc1 .Lpf_nok0
	s_add_u32 s98, s98, 0x100000
	s_addc_u32 s99, s99, 0
	v_mov_b32_e32 v100, v237
	v_add_u32_e32 v104, 0x8000, v237
	v_add_u32_e32 v108, 0x10000, v237
	v_add_u32_e32 v112, 0x18000, v237
	global_load_dwordx4 v[100:103], v100, s[98:99]
	global_load_dwordx4 v[104:107], v104, s[98:99]
	global_load_dwordx4 v[108:111], v108, s[98:99]
	global_load_dwordx4 v[112:115], v112, s[98:99]
	.Lpf_nok0:
	s_and_b64 vcc, exec, s[4:5]
	s_cbranch_vccnz .Lat_pv3
	ds_read_b128 v[208:211], v187 offset:256
	ds_read_b128 v[212:215], v187 offset:320
	ds_read_b128 v[36:39], v201
	ds_read_b128 v[40:43], v201 offset:2048
	ds_read_b128 v[44:47], v201 offset:4096
	ds_read_b128 v[48:51], v201 offset:6144
	ds_read_b128 v[52:55], v201 offset:8192
	ds_read_b128 v[56:59], v201 offset:10240
	ds_read_b128 v[60:63], v201 offset:12288
	ds_read_b128 v[64:67], v201 offset:14336
	s_waitcnt lgkmcnt(7)
	v_mfma_f32_16x16x32_bf16 v[176:179], v[36:39], v[208:211], v[176:179]
	ds_read_b128 v[68:71], v201 offset:16384
	s_waitcnt lgkmcnt(7)
	v_mfma_f32_16x16x32_bf16 v[172:175], v[40:43], v[208:211], v[172:175]
	ds_read_b128 v[72:75], v201 offset:18432
	s_waitcnt lgkmcnt(7)
	v_mfma_f32_16x16x32_bf16 v[168:171], v[44:47], v[208:211], v[168:171]
	ds_read_b128 v[76:79], v201 offset:20480
	s_waitcnt lgkmcnt(7)
	v_mfma_f32_16x16x32_bf16 v[164:167], v[48:51], v[208:211], v[164:167]
	ds_read_b128 v[80:83], v201 offset:22528
	s_waitcnt lgkmcnt(7)
	v_mfma_f32_16x16x32_bf16 v[160:163], v[52:55], v[208:211], v[160:163]
	ds_read_b128 v[84:87], v201 offset:24576
	s_waitcnt lgkmcnt(7)
	v_mfma_f32_16x16x32_bf16 v[156:159], v[56:59], v[208:211], v[156:159]
	ds_read_b128 v[88:91], v201 offset:26624
	s_waitcnt lgkmcnt(7)
	v_mfma_f32_16x16x32_bf16 v[152:155], v[60:63], v[208:211], v[152:155]
	ds_read_b128 v[92:95], v201 offset:28672
	s_waitcnt lgkmcnt(7)
	v_mfma_f32_16x16x32_bf16 v[148:151], v[64:67], v[208:211], v[148:151]
	ds_read_b128 v[96:99], v201 offset:30720
	s_waitcnt lgkmcnt(7)
	v_mfma_f32_16x16x32_bf16 v[144:147], v[68:71], v[208:211], v[144:147]
	ds_read_b128 v[36:39], v239
	s_waitcnt lgkmcnt(7)
	v_mfma_f32_16x16x32_bf16 v[140:143], v[72:75], v[208:211], v[140:143]
	ds_read_b128 v[40:43], v239 offset:2048
	s_waitcnt lgkmcnt(7)
	v_mfma_f32_16x16x32_bf16 v[136:139], v[76:79], v[208:211], v[136:139]
	ds_read_b128 v[44:47], v239 offset:4096
	s_waitcnt lgkmcnt(7)
	v_mfma_f32_16x16x32_bf16 v[132:135], v[80:83], v[208:211], v[132:135]
	ds_read_b128 v[48:51], v239 offset:6144
	s_waitcnt lgkmcnt(7)
	v_mfma_f32_16x16x32_bf16 v[128:131], v[84:87], v[208:211], v[128:131]
	ds_read_b128 v[52:55], v239 offset:8192
	s_waitcnt lgkmcnt(7)
	v_mfma_f32_16x16x32_bf16 v[124:127], v[88:91], v[208:211], v[124:127]
	ds_read_b128 v[56:59], v239 offset:10240
	s_waitcnt lgkmcnt(7)
	v_mfma_f32_16x16x32_bf16 v[120:123], v[92:95], v[208:211], v[120:123]
	ds_read_b128 v[60:63], v239 offset:12288
	s_waitcnt lgkmcnt(7)
	v_mfma_f32_16x16x32_bf16 v[116:119], v[96:99], v[208:211], v[116:119]
	ds_read_b128 v[64:67], v239 offset:14336
	s_waitcnt lgkmcnt(7)
	v_mfma_f32_16x16x32_bf16 v[176:179], v[36:39], v[212:215], v[176:179]
	ds_read_b128 v[68:71], v239 offset:16384
	s_waitcnt lgkmcnt(7)
	v_mfma_f32_16x16x32_bf16 v[172:175], v[40:43], v[212:215], v[172:175]
	ds_read_b128 v[72:75], v239 offset:18432
	s_waitcnt lgkmcnt(7)
	v_mfma_f32_16x16x32_bf16 v[168:171], v[44:47], v[212:215], v[168:171]
	ds_read_b128 v[76:79], v239 offset:20480
	s_waitcnt lgkmcnt(7)
	v_mfma_f32_16x16x32_bf16 v[164:167], v[48:51], v[212:215], v[164:167]
	ds_read_b128 v[80:83], v239 offset:22528
	s_waitcnt lgkmcnt(7)
	v_mfma_f32_16x16x32_bf16 v[160:163], v[52:55], v[212:215], v[160:163]
	ds_read_b128 v[84:87], v239 offset:24576
	s_waitcnt lgkmcnt(7)
	v_mfma_f32_16x16x32_bf16 v[156:159], v[56:59], v[212:215], v[156:159]
	ds_read_b128 v[88:91], v239 offset:26624
	s_waitcnt lgkmcnt(7)
	v_mfma_f32_16x16x32_bf16 v[152:155], v[60:63], v[212:215], v[152:155]
	ds_read_b128 v[92:95], v239 offset:28672
	s_waitcnt lgkmcnt(7)
	v_mfma_f32_16x16x32_bf16 v[148:151], v[64:67], v[212:215], v[148:151]
	ds_read_b128 v[96:99], v239 offset:30720
	s_waitcnt lgkmcnt(7)
	v_mfma_f32_16x16x32_bf16 v[144:147], v[68:71], v[212:215], v[144:147]
	s_waitcnt lgkmcnt(6)
	v_mfma_f32_16x16x32_bf16 v[140:143], v[72:75], v[212:215], v[140:143]
	s_waitcnt lgkmcnt(5)
	v_mfma_f32_16x16x32_bf16 v[136:139], v[76:79], v[212:215], v[136:139]
	s_waitcnt lgkmcnt(4)
	v_mfma_f32_16x16x32_bf16 v[132:135], v[80:83], v[212:215], v[132:135]
	s_waitcnt lgkmcnt(3)
	v_mfma_f32_16x16x32_bf16 v[128:131], v[84:87], v[212:215], v[128:131]
	s_waitcnt lgkmcnt(2)
	v_mfma_f32_16x16x32_bf16 v[124:127], v[88:91], v[212:215], v[124:127]
	s_waitcnt lgkmcnt(1)
	v_mfma_f32_16x16x32_bf16 v[120:123], v[92:95], v[212:215], v[120:123]
	s_waitcnt lgkmcnt(0)
	v_mfma_f32_16x16x32_bf16 v[116:119], v[96:99], v[212:215], v[116:119]
; #define LAS __attribute__((address_space(3)))
; #define LOADV(i) do { _Pragma("unroll") for (int j = 0; j < 4; ++j) st[j] = *(const u32x4*)(vbase + (j * 64 * 256 + (i) * 64) + voff); } while (0)
; #define STOREV() do { _Pragma("unroll") for (int j = 0; j < 4; ++j) *(LAS u32x4*)(vst + j * 64 * 144) = st[j]; } while (0)
; __device__ __forceinline__ void ph_attn(const Params& p, LAS unsigned char* lds) {
;     ...
; #pragma unroll 1
;         for (int i = 0; i < 4; ++i) {
;             __syncthreads(); STOREV(); __syncthreads();
;             if (i < 3) LOADV(i + 1);
;             if (active) {
; #pragma unroll
;                 for (int ks = 0; ks < 2; ++ks) {
;                     const bf16x8 pf = *(const LAS bf16x8*)(pw + fq * 8 + i * 128 + ks * 64);
; #pragma unroll
;                     for (int dt = 0; dt < 16; ++dt) {
;                         const bf16x8 vf = *(const LAS bf16x8*)(vrd + dt * 16 * 144 + ks * 64);
;                         oa[dt] = __builtin_amdgcn_mfma_f32_16x16x32_bf16(vf, pf, oa[dt], 0, 0, 0);
;                     }
;                 }
.Lat_pv3:
	s_waitcnt lgkmcnt(0)
	s_barrier
	s_cmp_eq_u32 s96, 1
	s_cbranch_scc1 .Lpf_v2
	s_waitcnt vmcnt(3)
	ds_write_b128 v199, v[240:243]
	s_waitcnt vmcnt(2)
	ds_write_b128 v199, v[244:247] offset:8192
	s_waitcnt vmcnt(1)
	ds_write_b128 v199, v[248:251] offset:16384
	s_waitcnt vmcnt(0)
	ds_write_b128 v199, v[252:255] offset:24576
	s_branch .Lpf_j2
	.Lpf_v2:
	s_waitcnt vmcnt(15)
	ds_write_b128 v199, v[240:243]
	s_waitcnt vmcnt(14)
	ds_write_b128 v199, v[244:247] offset:8192
	s_waitcnt vmcnt(13)
	ds_write_b128 v199, v[248:251] offset:16384
	s_waitcnt vmcnt(12)
	ds_write_b128 v199, v[252:255] offset:24576
	.Lpf_j2:
	s_waitcnt lgkmcnt(0)
	s_barrier
	s_cmp_eq_u32 s96, 0
	s_cbranch_scc1 .Lpf_nok1
	v_add_u32_e32 v240, 0x20000, v237
	v_add_u32_e32 v244, 0x28000, v237
	v_add_u32_e32 v248, 0x30000, v237
	v_add_u32_e32 v252, 0x38000, v237
	global_load_dwordx4 v[240:243], v240, s[98:99]
	global_load_dwordx4 v[244:247], v244, s[98:99]
	global_load_dwordx4 v[248:251], v248, s[98:99]
	global_load_dwordx4 v[252:255], v252, s[98:99]
	.Lpf_nok1:
	s_and_b64 vcc, exec, s[4:5]
	s_cbranch_vccnz .LBB0_1108
	ds_read_b128 v[208:211], v187 offset:384
	ds_read_b128 v[212:215], v187 offset:448
	ds_read_b128 v[36:39], v201
	ds_read_b128 v[40:43], v201 offset:2048
	ds_read_b128 v[44:47], v201 offset:4096
	ds_read_b128 v[48:51], v201 offset:6144
	ds_read_b128 v[52:55], v201 offset:8192
	ds_read_b128 v[56:59], v201 offset:10240
	ds_read_b128 v[60:63], v201 offset:12288
	ds_read_b128 v[64:67], v201 offset:14336
	s_waitcnt lgkmcnt(7)
	v_mfma_f32_16x16x32_bf16 v[176:179], v[36:39], v[208:211], v[176:179]
	ds_read_b128 v[68:71], v201 offset:16384
	s_waitcnt lgkmcnt(7)
	v_mfma_f32_16x16x32_bf16 v[172:175], v[40:43], v[208:211], v[172:175]
	ds_read_b128 v[72:75], v201 offset:18432
	s_waitcnt lgkmcnt(7)
	v_mfma_f32_16x16x32_bf16 v[168:171], v[44:47], v[208:211], v[168:171]
	ds_read_b128 v[76:79], v201 offset:20480
	s_waitcnt lgkmcnt(7)
	v_mfma_f32_16x16x32_bf16 v[164:167], v[48:51], v[208:211], v[164:167]
	ds_read_b128 v[80:83], v201 offset:22528
	s_waitcnt lgkmcnt(7)
	v_mfma_f32_16x16x32_bf16 v[160:163], v[52:55], v[208:211], v[160:163]
	ds_read_b128 v[84:87], v201 offset:24576
	s_waitcnt lgkmcnt(7)
	v_mfma_f32_16x16x32_bf16 v[156:159], v[56:59], v[208:211], v[156:159]
	ds_read_b128 v[88:91], v201 offset:26624
	s_waitcnt lgkmcnt(7)
	v_mfma_f32_16x16x32_bf16 v[152:155], v[60:63], v[208:211], v[152:155]
	ds_read_b128 v[92:95], v201 offset:28672
	s_waitcnt lgkmcnt(7)
	v_mfma_f32_16x16x32_bf16 v[148:151], v[64:67], v[208:211], v[148:151]
	ds_read_b128 v[96:99], v201 offset:30720
	s_waitcnt lgkmcnt(7)
	v_mfma_f32_16x16x32_bf16 v[144:147], v[68:71], v[208:211], v[144:147]
	ds_read_b128 v[36:39], v239
	s_waitcnt lgkmcnt(7)
	v_mfma_f32_16x16x32_bf16 v[140:143], v[72:75], v[208:211], v[140:143]
	ds_read_b128 v[40:43], v239 offset:2048
	s_waitcnt lgkmcnt(7)
	v_mfma_f32_16x16x32_bf16 v[136:139], v[76:79], v[208:211], v[136:139]
	ds_read_b128 v[44:47], v239 offset:4096
	s_waitcnt lgkmcnt(7)
	v_mfma_f32_16x16x32_bf16 v[132:135], v[80:83], v[208:211], v[132:135]
	ds_read_b128 v[48:51], v239 offset:6144
	s_waitcnt lgkmcnt(7)
	v_mfma_f32_16x16x32_bf16 v[128:131], v[84:87], v[208:211], v[128:131]
	ds_read_b128 v[52:55], v239 offset:8192
	s_waitcnt lgkmcnt(7)
	v_mfma_f32_16x16x32_bf16 v[124:127], v[88:91], v[208:211], v[124:127]
	ds_read_b128 v[56:59], v239 offset:10240
	s_waitcnt lgkmcnt(7)
	v_mfma_f32_16x16x32_bf16 v[120:123], v[92:95], v[208:211], v[120:123]
	ds_read_b128 v[60:63], v239 offset:12288
	s_waitcnt lgkmcnt(7)
	v_mfma_f32_16x16x32_bf16 v[116:119], v[96:99], v[208:211], v[116:119]
	ds_read_b128 v[64:67], v239 offset:14336
	s_waitcnt lgkmcnt(7)
	v_mfma_f32_16x16x32_bf16 v[176:179], v[36:39], v[212:215], v[176:179]
	ds_read_b128 v[68:71], v239 offset:16384
	s_waitcnt lgkmcnt(7)
	v_mfma_f32_16x16x32_bf16 v[172:175], v[40:43], v[212:215], v[172:175]
	ds_read_b128 v[72:75], v239 offset:18432
	s_waitcnt lgkmcnt(7)
	v_mfma_f32_16x16x32_bf16 v[168:171], v[44:47], v[212:215], v[168:171]
	ds_read_b128 v[76:79], v239 offset:20480
	s_waitcnt lgkmcnt(7)
	v_mfma_f32_16x16x32_bf16 v[164:167], v[48:51], v[212:215], v[164:167]
	ds_read_b128 v[80:83], v239 offset:22528
	s_waitcnt lgkmcnt(7)
	v_mfma_f32_16x16x32_bf16 v[160:163], v[52:55], v[212:215], v[160:163]
	ds_read_b128 v[84:87], v239 offset:24576
	s_waitcnt lgkmcnt(7)
	v_mfma_f32_16x16x32_bf16 v[156:159], v[56:59], v[212:215], v[156:159]
	ds_read_b128 v[88:91], v239 offset:26624
	s_waitcnt lgkmcnt(7)
	v_mfma_f32_16x16x32_bf16 v[152:155], v[60:63], v[212:215], v[152:155]
	ds_read_b128 v[92:95], v239 offset:28672
	s_waitcnt lgkmcnt(7)
	v_mfma_f32_16x16x32_bf16 v[148:151], v[64:67], v[212:215], v[148:151]
	ds_read_b128 v[96:99], v239 offset:30720
	s_waitcnt lgkmcnt(7)
	v_mfma_f32_16x16x32_bf16 v[144:147], v[68:71], v[212:215], v[144:147]
	s_waitcnt lgkmcnt(6)
	v_mfma_f32_16x16x32_bf16 v[140:143], v[72:75], v[212:215], v[140:143]
	s_waitcnt lgkmcnt(5)
	v_mfma_f32_16x16x32_bf16 v[136:139], v[76:79], v[212:215], v[136:139]
	s_waitcnt lgkmcnt(4)
	v_mfma_f32_16x16x32_bf16 v[132:135], v[80:83], v[212:215], v[132:135]
	s_waitcnt lgkmcnt(3)
	v_mfma_f32_16x16x32_bf16 v[128:131], v[84:87], v[212:215], v[128:131]
	s_waitcnt lgkmcnt(2)
	v_mfma_f32_16x16x32_bf16 v[124:127], v[88:91], v[212:215], v[124:127]
	s_waitcnt lgkmcnt(1)
	v_mfma_f32_16x16x32_bf16 v[120:123], v[92:95], v[212:215], v[120:123]
	s_waitcnt lgkmcnt(0)
	v_mfma_f32_16x16x32_bf16 v[116:119], v[96:99], v[212:215], v[116:119]
; __device__ __forceinline__ unsigned cvt_pk_bf16(float lo, float hi) { f32x2 f = {lo, hi}; bf16x2_t v = __builtin_convertvector(f, bf16x2_t); return __builtin_bit_cast(unsigned, v); }
; __device__ __forceinline__ void ph_attn(const Params& p, LAS unsigned char* lds) {
;     ...
;         if (active) {
;             bf16_t* dst = ao + (size_t)(r0 + w * 16 + fr) * D + h * 256 + fq * 4;
; #pragma unroll
;             for (int dt = 0; dt < 16; ++dt) { u32x2 wv; wv.x = cvt_pk_bf16(oa[dt][0] * linv, oa[dt][1] * linv); wv.y = cvt_pk_bf16(oa[dt][2] * linv, oa[dt][3] * linv); *(u32x2*)(dst + dt * 16) = wv; }
;         }
.LBB0_1108:
	s_and_b64 vcc, exec, s[12:13]
	s_cbranch_vccz .LBB0_1083
	v_lshlrev_b64 v[2:3], 11, v[190:191]
	v_lshl_add_u64 v[2:3], s[8:9], 0, v[2:3]
	v_lshl_add_u64 v[2:3], s[10:11], 1, v[2:3]
	v_mov_b32_e32 v189, v0
	s_nop 0
	v_pk_mul_f32 v[36:37], v[192:193], v[176:177] op_sel_hi:[0,1]
	v_pk_mul_f32 v[38:39], v[192:193], v[178:179] op_sel_hi:[0,1]
	v_lshl_add_u64 v[2:3], v[2:3], 0, v[188:189]
	v_cvt_pk_bf16_f32 v36, v36, v37
	v_cvt_pk_bf16_f32 v37, v38, v39
	global_store_dwordx2 v[2:3], v[36:37], off
	v_pk_mul_f32 v[36:37], v[192:193], v[172:173] op_sel_hi:[0,1]
	v_pk_mul_f32 v[38:39], v[192:193], v[174:175] op_sel_hi:[0,1]
	v_cvt_pk_bf16_f32 v36, v36, v37
	v_cvt_pk_bf16_f32 v37, v38, v39
	global_store_dwordx2 v[2:3], v[36:37], off offset:32
	v_pk_mul_f32 v[36:37], v[192:193], v[168:169] op_sel_hi:[0,1]
	v_pk_mul_f32 v[38:39], v[192:193], v[170:171] op_sel_hi:[0,1]
	v_cvt_pk_bf16_f32 v36, v36, v37
	v_cvt_pk_bf16_f32 v37, v38, v39
	global_store_dwordx2 v[2:3], v[36:37], off offset:64
	v_pk_mul_f32 v[36:37], v[192:193], v[164:165] op_sel_hi:[0,1]
	v_pk_mul_f32 v[38:39], v[192:193], v[166:167] op_sel_hi:[0,1]
	v_cvt_pk_bf16_f32 v36, v36, v37
	v_cvt_pk_bf16_f32 v37, v38, v39
	global_store_dwordx2 v[2:3], v[36:37], off offset:96
	v_pk_mul_f32 v[36:37], v[192:193], v[160:161] op_sel_hi:[0,1]
	v_pk_mul_f32 v[38:39], v[192:193], v[162:163] op_sel_hi:[0,1]
	v_cvt_pk_bf16_f32 v36, v36, v37
	v_cvt_pk_bf16_f32 v37, v38, v39
	global_store_dwordx2 v[2:3], v[36:37], off offset:128
	v_pk_mul_f32 v[36:37], v[192:193], v[156:157] op_sel_hi:[0,1]
	v_pk_mul_f32 v[38:39], v[192:193], v[158:159] op_sel_hi:[0,1]
	v_cvt_pk_bf16_f32 v36, v36, v37
	v_cvt_pk_bf16_f32 v37, v38, v39
	global_store_dwordx2 v[2:3], v[36:37], off offset:160
	v_pk_mul_f32 v[36:37], v[192:193], v[152:153] op_sel_hi:[0,1]
	v_pk_mul_f32 v[38:39], v[192:193], v[154:155] op_sel_hi:[0,1]
	v_cvt_pk_bf16_f32 v36, v36, v37
	v_cvt_pk_bf16_f32 v37, v38, v39
	global_store_dwordx2 v[2:3], v[36:37], off offset:192
	v_pk_mul_f32 v[36:37], v[192:193], v[148:149] op_sel_hi:[0,1]
	v_pk_mul_f32 v[38:39], v[192:193], v[150:151] op_sel_hi:[0,1]
	v_cvt_pk_bf16_f32 v36, v36, v37
	v_cvt_pk_bf16_f32 v37, v38, v39
	global_store_dwordx2 v[2:3], v[36:37], off offset:224
	v_pk_mul_f32 v[36:37], v[192:193], v[144:145] op_sel_hi:[0,1]
	v_pk_mul_f32 v[38:39], v[192:193], v[146:147] op_sel_hi:[0,1]
	v_cvt_pk_bf16_f32 v36, v36, v37
	v_cvt_pk_bf16_f32 v37, v38, v39
	global_store_dwordx2 v[2:3], v[36:37], off offset:256
	v_pk_mul_f32 v[36:37], v[192:193], v[140:141] op_sel_hi:[0,1]
	v_pk_mul_f32 v[38:39], v[192:193], v[142:143] op_sel_hi:[0,1]
	v_cvt_pk_bf16_f32 v36, v36, v37
	v_cvt_pk_bf16_f32 v37, v38, v39
	global_store_dwordx2 v[2:3], v[36:37], off offset:288
	v_pk_mul_f32 v[36:37], v[192:193], v[136:137] op_sel_hi:[0,1]
	v_pk_mul_f32 v[38:39], v[192:193], v[138:139] op_sel_hi:[0,1]
	v_cvt_pk_bf16_f32 v36, v36, v37
	v_cvt_pk_bf16_f32 v37, v38, v39
	global_store_dwordx2 v[2:3], v[36:37], off offset:320
	v_pk_mul_f32 v[36:37], v[192:193], v[132:133] op_sel_hi:[0,1]
	v_pk_mul_f32 v[38:39], v[192:193], v[134:135] op_sel_hi:[0,1]
	v_cvt_pk_bf16_f32 v36, v36, v37
	v_cvt_pk_bf16_f32 v37, v38, v39
	global_store_dwordx2 v[2:3], v[36:37], off offset:352
	v_pk_mul_f32 v[36:37], v[192:193], v[128:129] op_sel_hi:[0,1]
	v_pk_mul_f32 v[38:39], v[192:193], v[130:131] op_sel_hi:[0,1]
	v_cvt_pk_bf16_f32 v36, v36, v37
	v_cvt_pk_bf16_f32 v37, v38, v39
	global_store_dwordx2 v[2:3], v[36:37], off offset:384
	v_pk_mul_f32 v[36:37], v[192:193], v[124:125] op_sel_hi:[0,1]
	v_pk_mul_f32 v[38:39], v[192:193], v[126:127] op_sel_hi:[0,1]
	v_cvt_pk_bf16_f32 v36, v36, v37
	v_cvt_pk_bf16_f32 v37, v38, v39
	global_store_dwordx2 v[2:3], v[36:37], off offset:416
	v_pk_mul_f32 v[36:37], v[192:193], v[120:121] op_sel_hi:[0,1]
	v_pk_mul_f32 v[38:39], v[192:193], v[122:123] op_sel_hi:[0,1]
	v_cvt_pk_bf16_f32 v36, v36, v37
	v_cvt_pk_bf16_f32 v37, v38, v39
	global_store_dwordx2 v[2:3], v[36:37], off offset:448
	v_pk_mul_f32 v[36:37], v[192:193], v[116:117] op_sel_hi:[0,1]
	v_pk_mul_f32 v[38:39], v[192:193], v[118:119] op_sel_hi:[0,1]
	v_cvt_pk_bf16_f32 v36, v36, v37
	v_cvt_pk_bf16_f32 v37, v38, v39
	global_store_dwordx2 v[2:3], v[36:37], off offset:480
	s_branch .LBB0_1083
